# hot-loop instruction-fetch alignment: 64-byte alignment of the attention sub-tile loop head and the mLSTM chunk loop head
# baseline (speedup 1.0000x reference)
.LBB0_157:
	s_sub_i32 s14, s14, 64
	v_add_u32_e32 v236, 0xffffff00, v236
	v_add_u32_e32 v235, 0xffffff80, v235
	s_cmpk_eq_i32 s14, 0xff00
	v_add_u32_e32 v1, 0xffffdc00, v1
	s_cbranch_scc1 .LBB0_147
	.p2align	6

.LBB0_206:
	s_or_b64 exec, exec, s[12:13]
	s_add_u32 s82, s82, 64
	s_addc_u32 s83, s83, 0
	s_add_i32 s56, s56, 4
	s_add_u32 s4, s4, 0x20000
	s_addc_u32 s31, s31, 0
	s_add_u32 s88, s88, 0x400
	s_addc_u32 s89, s89, 0
	s_add_u32 s57, s57, 0x80
	s_waitcnt lgkmcnt(0)
	s_barrier
	s_addc_u32 s14, s14, 0
	s_cmpk_lg_i32 s82, 0x800
	s_cbranch_scc0 .LBB0_135
	.p2align	6
